# non-temporal hints: GLA V loads, attention Q loads (each element read once)
# baseline (speedup 1.0000x reference)
; #define LAS __attribute__((address_space(3)))
; #define GAS __attribute__((address_space(1)))
; __device__ __forceinline__ bf16_t f2bf(float x) { return (bf16_t)(cvt_pk_bf16(x, x) & 0xffffu); }
; __device__ __forceinline__ float bf2f(bf16_t v) { return __uint_as_float((unsigned)v << 16); }
; __device__ __forceinline__ u32x4 pack8(const float* v) { u32x4 w; w.x = cvt_pk_bf16(v[0], v[1]); w.y = cvt_pk_bf16(v[2], v[3]); w.z = cvt_pk_bf16(v[4], v[5]); w.w = cvt_pk_bf16(v[6], v[7]); return w; }
; template <int DK, int DVS, bool RET> ...
;     ...
;             for (int t = 0; t < TPW; ++t)
; #pragma unroll
;                 for (int j = 0; j < 4; ++j) STB[(tv * 16 + quad * 4 + j) * LK + (kt0 + t) * 16 + l16] = f2bf(st[t][j]);
;             { const int p = tid >> 3, vg = tid & 7; const long row = R0 + (dir ? 63 - p : p); vraw = *(const GAS vvec_t*)(Vg + row * ldv + vcol0 + vg * VPT); }
;             float bl;
;             if constexpr (RET) {
;                 static_assert(!RET || DK == 256, "retention prep: 64 x 256 = 2048 eight-wide items, four per thread");
;                 bl = 64.f * lg;
; #pragma unroll
;                 for (int j = 0; j < 4; ++j) { const int it = tid + 512 * j, p = it & 63, k0 = (it >> 6) * 8; const float bb = (float)(p + 1) * lg;
;                     const float eq = __expf(bb), ek = __expf(-bb); float a[8], c[8];
; #pragma unroll
;                     for (int e = 0; e < 8; ++e) { a[e] = bf2f((bf16_t)qv[j][e]) * eq; c[e] = bf2f((bf16_t)kv[j][e]) * ek; }
;                     *(LAS u32x4*)(QD + p * LK + k0) = pack8(a); *(LAS u32x4*)(KD + p * LK + k0) = pack8(c); }
;             } else {
;                 float c = 0.f;
; #pragma unroll
;                 for (int i = 0; i < PPT; ++i) c += lc[i];
;                 TOT[pg * 128 + kx] = c;
;                 GLA_BAR();
;                 float off = 0.f; bl = 0.f;
; #pragma unroll
;                 for (int g = 0; g < NPG; ++g) { const float t = TOT[g * 128 + kx]; if (g < pg) off += t; bl += t; }
;                 float bb = off;
; #pragma unroll
;                 for (int i = 0; i < PPT; ++i) { const int p = pg * PPT + i;
;                     const float qf = bf2f(qr[i]), kf = 1.f - __expf(lc[i]); bb += lc[i];
;                     QD[p * LK + kx] = f2bf(qf * __expf(bb)); KD[p * LK + kx] = f2bf(kf * __expf(-bb)); }
.LBB0_54:
	v_cvt_pk_bf16_f32 v71, v71, s0
	s_waitcnt lgkmcnt(0)
	s_barrier
	ds_write_b16 v213, v71 offset:272
	v_cvt_pk_bf16_f32 v71, v72, s0
	s_waitcnt vmcnt(0)
	v_add_f32_e32 v72, 0, v132
	v_add_f32_e32 v72, v134, v72
	v_add_f32_e32 v72, v136, v72
	v_add_f32_e32 v72, v138, v72
	v_add_f32_e32 v72, v140, v72
	s_cmp_gt_u32 s36, 3
	v_add_f32_e32 v72, v142, v72
	s_cselect_b32 s40, 0x47, 3
	v_add_f32_e32 v72, v147, v72
	s_add_i32 s40, s40, s41
	v_add_f32_e32 v72, v151, v72
	s_and_b64 s[44:45], s[30:31], exec
	v_add_f32_e32 v72, v210, v72
	s_cselect_b32 s40, s36, s40
	v_add_f32_e32 v72, v220, v72
	s_lshl_b32 s40, s40, 6
	ds_write_b16 v213, v71 offset:544
	v_cvt_pk_bf16_f32 v71, v73, s0
	v_add_f32_e32 v72, v222, v72
	s_ashr_i32 s45, s40, 31
	ds_write_b16 v213, v71 offset:816
	v_cvt_pk_bf16_f32 v71, v74, s0
	v_add_f32_e32 v72, v224, v72
	ds_write_b16 v214, v71
	v_cvt_pk_bf16_f32 v71, v75, s0
	s_add_u32 s44, s42, s40
	v_add_f32_e32 v72, v226, v72
	ds_write_b16 v214, v71 offset:272
	v_cvt_pk_bf16_f32 v71, v234, s0
	v_cvt_pk_bf16_f32 v70, v70, s0
	s_addc_u32 s45, s43, s45
	v_add_f32_e32 v72, v228, v72
	ds_write_b16 v214, v71 offset:544
	ds_write_b16 v214, v70 offset:816
	v_lshl_add_u64 v[70:71], s[44:45], 0, v[56:57]
	v_add_f32_e32 v72, v230, v72
	v_cvt_pk_bf16_f32 v110, v0, s0
	v_lshlrev_b64 v[70:71], 11, v[70:71]
	v_add_f32_e32 v72, v232, v72
	ds_write_b16 v213, v110
	v_lshl_add_u64 v[70:71], v[58:59], 0, v[70:71]
	ds_write_b32 v152, v72
	global_load_dwordx2 v[70:71], v[70:71], off nt
	s_waitcnt lgkmcnt(0)
	s_barrier
	ds_read2st64_b32 v[72:73], v153 offset1:2
	v_mul_f32_e32 v112, 0x3fb8aa3b, v132
	v_exp_f32_e32 v112, v112
	s_waitcnt lgkmcnt(0)
	v_add_f32_e32 v72, 0, v72
	v_cndmask_b32_e64 v74, 0, v72, s[6:7]
	v_add_f32_e32 v75, v73, v74
	v_cndmask_b32_e64 v110, v74, v75, s[8:9]
	ds_read2st64_b32 v[74:75], v153 offset0:4 offset1:6
	v_sub_f32_e32 v112, 1.0, v112
	s_waitcnt lgkmcnt(0)
	v_add_f32_e32 v111, v74, v110
	v_cndmask_b32_e64 v110, v110, v111, s[10:11]
	v_add_f32_e32 v111, v75, v110
	v_cndmask_b32_e64 v110, v110, v111, s[12:13]
	v_add_f32_e32 v110, v132, v110
	v_mul_f32_e32 v113, 0x3fb8aa3b, v110
	v_exp_f32_e32 v113, v113
	v_lshlrev_b32_e32 v111, 16, v133
	v_mul_f32_e32 v111, v113, v111
	v_cvt_pk_bf16_f32 v111, v111, s0
	ds_write_b16 v160, v111
	v_mul_f32_e32 v111, 0xbfb8aa3b, v110
	v_exp_f32_e32 v111, v111
	v_add_f32_e32 v110, v134, v110
	v_mul_f32_e32 v113, 0x3fb8aa3b, v110
	v_exp_f32_e32 v113, v113
	v_mul_f32_e32 v111, v112, v111
	v_cvt_pk_bf16_f32 v111, v111, s0
	ds_write_b16 v161, v111
	v_lshlrev_b32_e32 v111, 16, v135
	v_mul_f32_e32 v111, v113, v111
	v_mul_f32_e32 v112, 0x3fb8aa3b, v134
	v_cvt_pk_bf16_f32 v111, v111, s0
	v_exp_f32_e32 v112, v112
	ds_write_b16 v163, v111
	v_mul_f32_e32 v111, 0xbfb8aa3b, v110
	v_exp_f32_e32 v111, v111
	v_add_f32_e32 v110, v136, v110
	v_mul_f32_e32 v113, 0x3fb8aa3b, v110
	v_sub_f32_e32 v112, 1.0, v112
	v_exp_f32_e32 v113, v113
	v_mul_f32_e32 v111, v112, v111
	v_cvt_pk_bf16_f32 v111, v111, s0
	ds_write_b16 v164, v111
	v_lshlrev_b32_e32 v111, 16, v137
	v_mul_f32_e32 v111, v113, v111
	v_mul_f32_e32 v112, 0x3fb8aa3b, v136
	v_cvt_pk_bf16_f32 v111, v111, s0
	v_exp_f32_e32 v112, v112
	ds_write_b16 v165, v111
	v_mul_f32_e32 v111, 0xbfb8aa3b, v110
	v_exp_f32_e32 v111, v111
	v_add_f32_e32 v110, v138, v110
	v_mul_f32_e32 v113, 0x3fb8aa3b, v110
	v_sub_f32_e32 v112, 1.0, v112
	v_exp_f32_e32 v113, v113
	v_mul_f32_e32 v111, v112, v111
	v_cvt_pk_bf16_f32 v111, v111, s0
	ds_write_b16 v166, v111
	v_lshlrev_b32_e32 v111, 16, v139
	v_mul_f32_e32 v111, v113, v111
	v_mul_f32_e32 v112, 0x3fb8aa3b, v138
	v_cvt_pk_bf16_f32 v111, v111, s0
	v_exp_f32_e32 v112, v112
	ds_write_b16 v167, v111
	v_mul_f32_e32 v111, 0xbfb8aa3b, v110
	v_exp_f32_e32 v111, v111
	v_add_f32_e32 v110, v140, v110
	v_mul_f32_e32 v113, 0x3fb8aa3b, v110
	v_sub_f32_e32 v112, 1.0, v112
	v_exp_f32_e32 v113, v113
	v_mul_f32_e32 v111, v112, v111
	v_cvt_pk_bf16_f32 v111, v111, s0
	ds_write_b16 v168, v111
	v_lshlrev_b32_e32 v111, 16, v141
	v_mul_f32_e32 v111, v113, v111
	v_mul_f32_e32 v112, 0x3fb8aa3b, v140
	v_cvt_pk_bf16_f32 v111, v111, s0
	v_exp_f32_e32 v112, v112
	ds_write_b16 v169, v111
	v_mul_f32_e32 v111, 0xbfb8aa3b, v110
	v_exp_f32_e32 v111, v111
	v_add_f32_e32 v110, v142, v110
	v_mul_f32_e32 v113, 0x3fb8aa3b, v110
	v_sub_f32_e32 v112, 1.0, v112
	v_exp_f32_e32 v113, v113
	v_mul_f32_e32 v111, v112, v111
	v_cvt_pk_bf16_f32 v111, v111, s0
	ds_write_b16 v170, v111
	v_lshlrev_b32_e32 v111, 16, v143
	v_mul_f32_e32 v111, v113, v111
	v_mul_f32_e32 v112, 0x3fb8aa3b, v142
	v_cvt_pk_bf16_f32 v111, v111, s0
	v_exp_f32_e32 v112, v112
	ds_write_b16 v171, v111
	v_mul_f32_e32 v111, 0xbfb8aa3b, v110
	v_exp_f32_e32 v111, v111
	v_add_f32_e32 v110, v147, v110
	v_mul_f32_e32 v113, 0x3fb8aa3b, v110
	v_sub_f32_e32 v112, 1.0, v112
	v_exp_f32_e32 v113, v113
	v_mul_f32_e32 v111, v112, v111
	v_cvt_pk_bf16_f32 v111, v111, s0
; __device__ __forceinline__ bf16_t f2bf(float x) { return (bf16_t)(cvt_pk_bf16(x, x) & 0xffffu); }
; __device__ __forceinline__ float bf2f(bf16_t v) { return __uint_as_float((unsigned)v << 16); }
; template <int DK, int DVS, bool RET> ...
;     ...
;                 float bb = off;
; #pragma unroll
;                 for (int i = 0; i < PPT; ++i) { const int p = pg * PPT + i;
;                     const float qf = bf2f(qr[i]), kf = 1.f - __expf(lc[i]); bb += lc[i];
;                     QD[p * LK + kx] = f2bf(qf * __expf(bb)); KD[p * LK + kx] = f2bf(kf * __expf(-bb)); }
;             }
;             if (pg == 0) EL[kx] = __expf(bl);
	ds_write_b16 v172, v111
	v_lshlrev_b32_e32 v111, 16, v150
	v_mul_f32_e32 v111, v113, v111
	v_mul_f32_e32 v112, 0x3fb8aa3b, v147
	v_cvt_pk_bf16_f32 v111, v111, s0
	v_exp_f32_e32 v112, v112
	ds_write_b16 v173, v111
	v_mul_f32_e32 v111, 0xbfb8aa3b, v110
	v_exp_f32_e32 v111, v111
	v_add_f32_e32 v110, v151, v110
	v_mul_f32_e32 v113, 0x3fb8aa3b, v110
	v_sub_f32_e32 v112, 1.0, v112
	v_exp_f32_e32 v113, v113
	v_mul_f32_e32 v111, v112, v111
	v_cvt_pk_bf16_f32 v111, v111, s0
	ds_write_b16 v174, v111
	v_lshlrev_b32_e32 v111, 16, v162
	v_mul_f32_e32 v111, v113, v111
	v_mul_f32_e32 v112, 0x3fb8aa3b, v151
	v_cvt_pk_bf16_f32 v111, v111, s0
	v_exp_f32_e32 v112, v112
	ds_write_b16 v175, v111
	v_mul_f32_e32 v111, 0xbfb8aa3b, v110
	v_exp_f32_e32 v111, v111
	v_add_f32_e32 v110, v210, v110
	v_mul_f32_e32 v113, 0x3fb8aa3b, v110
	v_sub_f32_e32 v112, 1.0, v112
	v_exp_f32_e32 v113, v113
	v_mul_f32_e32 v111, v112, v111
	v_cvt_pk_bf16_f32 v111, v111, s0
	ds_write_b16 v176, v111
	v_lshlrev_b32_e32 v111, 16, v217
	v_mul_f32_e32 v111, v113, v111
	v_mul_f32_e32 v112, 0x3fb8aa3b, v210
	v_cvt_pk_bf16_f32 v111, v111, s0
	v_exp_f32_e32 v112, v112
	ds_write_b16 v177, v111
	v_mul_f32_e32 v111, 0xbfb8aa3b, v110
	v_exp_f32_e32 v111, v111
	v_add_f32_e32 v110, v220, v110
	v_mul_f32_e32 v113, 0x3fb8aa3b, v110
	v_sub_f32_e32 v112, 1.0, v112
	v_exp_f32_e32 v113, v113
	v_mul_f32_e32 v111, v112, v111
	v_cvt_pk_bf16_f32 v111, v111, s0
	ds_write_b16 v178, v111
	v_lshlrev_b32_e32 v111, 16, v221
	v_mul_f32_e32 v111, v113, v111
	v_mul_f32_e32 v112, 0x3fb8aa3b, v220
	v_cvt_pk_bf16_f32 v111, v111, s0
	v_exp_f32_e32 v112, v112
	ds_write_b16 v179, v111
	v_mul_f32_e32 v111, 0xbfb8aa3b, v110
	v_exp_f32_e32 v111, v111
	v_add_f32_e32 v110, v222, v110
	v_mul_f32_e32 v113, 0x3fb8aa3b, v110
	v_sub_f32_e32 v112, 1.0, v112
	v_exp_f32_e32 v113, v113
	v_mul_f32_e32 v111, v112, v111
	v_cvt_pk_bf16_f32 v111, v111, s0
	ds_write_b16 v180, v111
	v_lshlrev_b32_e32 v111, 16, v223
	v_mul_f32_e32 v111, v113, v111
	v_mul_f32_e32 v112, 0x3fb8aa3b, v222
	v_cvt_pk_bf16_f32 v111, v111, s0
	v_exp_f32_e32 v112, v112
	ds_write_b16 v181, v111
	v_mul_f32_e32 v111, 0xbfb8aa3b, v110
	v_exp_f32_e32 v111, v111
	v_add_f32_e32 v110, v224, v110
	v_mul_f32_e32 v113, 0x3fb8aa3b, v110
	v_sub_f32_e32 v112, 1.0, v112
	v_exp_f32_e32 v113, v113
	v_mul_f32_e32 v111, v112, v111
	v_cvt_pk_bf16_f32 v111, v111, s0
	ds_write_b16 v182, v111
	v_lshlrev_b32_e32 v111, 16, v225
	v_mul_f32_e32 v111, v113, v111
	v_mul_f32_e32 v112, 0x3fb8aa3b, v224
	v_cvt_pk_bf16_f32 v111, v111, s0
	v_exp_f32_e32 v112, v112
	ds_write_b16 v183, v111
	v_mul_f32_e32 v111, 0xbfb8aa3b, v110
	v_exp_f32_e32 v111, v111
	v_add_f32_e32 v110, v226, v110
	v_mul_f32_e32 v113, 0x3fb8aa3b, v110
	v_sub_f32_e32 v112, 1.0, v112
	v_exp_f32_e32 v113, v113
	v_mul_f32_e32 v111, v112, v111
	v_cvt_pk_bf16_f32 v111, v111, s0
	ds_write_b16 v184, v111
	v_lshlrev_b32_e32 v111, 16, v227
	v_mul_f32_e32 v111, v113, v111
	v_mul_f32_e32 v112, 0x3fb8aa3b, v226
	v_cvt_pk_bf16_f32 v111, v111, s0
	v_exp_f32_e32 v112, v112
	ds_write_b16 v185, v111
	v_mul_f32_e32 v111, 0xbfb8aa3b, v110
	v_exp_f32_e32 v111, v111
	v_add_f32_e32 v110, v228, v110
	v_mul_f32_e32 v113, 0x3fb8aa3b, v110
	v_sub_f32_e32 v112, 1.0, v112
	v_exp_f32_e32 v113, v113
	v_mul_f32_e32 v111, v112, v111
	v_cvt_pk_bf16_f32 v111, v111, s0
	ds_write_b16 v199, v111
	v_lshlrev_b32_e32 v111, 16, v229
	v_mul_f32_e32 v111, v113, v111
	v_mul_f32_e32 v112, 0x3fb8aa3b, v228
	v_cvt_pk_bf16_f32 v111, v111, s0
	v_exp_f32_e32 v112, v112
	ds_write_b16 v200, v111
	v_mul_f32_e32 v111, 0xbfb8aa3b, v110
	v_exp_f32_e32 v111, v111
	v_add_f32_e32 v110, v230, v110
	v_mul_f32_e32 v113, 0x3fb8aa3b, v110
	v_sub_f32_e32 v112, 1.0, v112
	v_exp_f32_e32 v113, v113
	v_mul_f32_e32 v111, v112, v111
	v_cvt_pk_bf16_f32 v111, v111, s0
	ds_write_b16 v201, v111
	v_lshlrev_b32_e32 v111, 16, v231
	v_mul_f32_e32 v111, v113, v111
	v_mul_f32_e32 v112, 0x3fb8aa3b, v230
	v_cvt_pk_bf16_f32 v111, v111, s0
	v_exp_f32_e32 v112, v112
	ds_write_b16 v202, v111
	v_mul_f32_e32 v111, 0xbfb8aa3b, v110
	v_exp_f32_e32 v111, v111
	v_sub_f32_e32 v112, 1.0, v112
	v_add_f32_e32 v110, v232, v110
	v_mul_f32_e32 v113, 0x3fb8aa3b, v110
	v_mul_f32_e32 v111, v112, v111
	v_mul_f32_e32 v112, 0x3fb8aa3b, v232
	v_exp_f32_e32 v112, v112
	v_mul_f32_e32 v110, 0xbfb8aa3b, v110
	v_exp_f32_e32 v113, v113
	v_exp_f32_e32 v110, v110
	v_cvt_pk_bf16_f32 v111, v111, s0
	ds_write_b16 v203, v111
	v_lshlrev_b32_e32 v111, 16, v233
	v_sub_f32_e32 v112, 1.0, v112
	v_mul_f32_e32 v111, v113, v111
	v_mul_f32_e32 v110, v112, v110
	v_cvt_pk_bf16_f32 v111, v111, s0
	v_cvt_pk_bf16_f32 v110, v110, s0
	ds_write_b16 v204, v111
	ds_write_b16 v205, v110
	s_and_saveexec_b64 s[46:47], vcc
	s_cbranch_execz .LBB0_56
	v_add_f32_e32 v72, v72, v73
	v_add_f32_e32 v72, v72, v74
	v_add_f32_e32 v72, v72, v75
	v_mul_f32_e32 v72, 0x3fb8aa3b, v72
	v_exp_f32_e32 v72, v72
	ds_write_b32 v154, v72

; #define LAS __attribute__((address_space(3)))
; #define GAS __attribute__((address_space(1)))
; __device__ __forceinline__ bf16_t f2bf(float x) { return (bf16_t)(cvt_pk_bf16(x, x) & 0xffffu); }
; __device__ __forceinline__ float bf2f(bf16_t v) { return __uint_as_float((unsigned)v << 16); }
; __device__ __forceinline__ u32x4 pack8(const float* v) { u32x4 w; w.x = cvt_pk_bf16(v[0], v[1]); w.y = cvt_pk_bf16(v[2], v[3]); w.z = cvt_pk_bf16(v[4], v[5]); w.w = cvt_pk_bf16(v[6], v[7]); return w; }
; template <int DK, int DVS, bool RET> ...
;     ...
;                 for (int j = 0; j < 4; ++j) STB[(tv * 16 + quad * 4 + j) * LK + (kt0 + t) * 16 + l16] = f2bf(st[t][j]);
;             { const int p = tid >> 3, vg = tid & 7; const long row = R0 + (dir ? 63 - p : p); vraw = *(const GAS vvec_t*)(Vg + row * ldv + vcol0 + vg * VPT); }
;             float bl;
;             if constexpr (RET) {
;                 static_assert(!RET || DK == 256, "retention prep: 64 x 256 = 2048 eight-wide items, four per thread");
;                 bl = 64.f * lg;
; #pragma unroll
;                 for (int j = 0; j < 4; ++j) { const int it = tid + 512 * j, p = it & 63, k0 = (it >> 6) * 8; const float bb = (float)(p + 1) * lg;
;                     const float eq = __expf(bb), ek = __expf(-bb); float a[8], c[8];
; #pragma unroll
;                     for (int e = 0; e < 8; ++e) { a[e] = bf2f((bf16_t)qv[j][e]) * eq; c[e] = bf2f((bf16_t)kv[j][e]) * ek; }
;                     *(LAS u32x4*)(QD + p * LK + k0) = pack8(a); *(LAS u32x4*)(KD + p * LK + k0) = pack8(c); }
.LBB0_71:
	v_cvt_pk_bf16_f32 v64, v56, s0
	s_cmp_gt_u32 s45, 3
	s_cselect_b32 s30, 0x47, 3
	s_add_i32 s36, s30, s42
	s_and_b64 s[30:31], s[22:23], exec
	s_cselect_b32 s30, s45, s36
	s_lshl_b32 s30, s30, 6
	s_ashr_i32 s31, s30, 31
	s_add_u32 s30, s44, s30
	s_addc_u32 s31, s43, s31
	v_lshl_add_u64 v[214:215], s[30:31], 0, v[96:97]
	v_lshlrev_b64 v[214:215], 12, v[214:215]
	v_lshl_add_u64 v[214:215], v[98:99], 0, v[214:215]
	global_load_dwordx4 v[212:215], v[214:215], off nt
	s_waitcnt lgkmcnt(0)
	s_barrier
	ds_write_b16 v210, v64
	v_cvt_pk_bf16_f32 v64, v57, s0
	ds_write_b16 v210, v64 offset:528
	v_cvt_pk_bf16_f32 v64, v58, s0
	ds_write_b16 v210, v64 offset:1056
	v_cvt_pk_bf16_f32 v64, v59, s0
	ds_write_b16 v210, v64 offset:1584
	v_cvt_pk_bf16_f32 v64, v60, s0
	ds_write_b16 v210, v64 offset:32
	v_cvt_pk_bf16_f32 v64, v61, s0
	ds_write_b16 v210, v64 offset:560
	v_cvt_pk_bf16_f32 v64, v62, s0
	ds_write_b16 v210, v64 offset:1088
	v_cvt_pk_bf16_f32 v64, v63, s0
	ds_write_b16 v210, v64 offset:1616
	v_cvt_pk_bf16_f32 v64, v48, s0
	ds_write_b16 v210, v64 offset:64
	v_cvt_pk_bf16_f32 v64, v49, s0
	ds_write_b16 v210, v64 offset:592
	v_cvt_pk_bf16_f32 v64, v50, s0
	ds_write_b16 v210, v64 offset:1120
	v_cvt_pk_bf16_f32 v64, v51, s0
	ds_write_b16 v210, v64 offset:1648
	v_cvt_pk_bf16_f32 v64, v52, s0
	ds_write_b16 v210, v64 offset:96
	v_cvt_pk_bf16_f32 v64, v53, s0
	ds_write_b16 v210, v64 offset:624
	v_cvt_pk_bf16_f32 v64, v54, s0
	ds_write_b16 v210, v64 offset:1152
	v_cvt_pk_bf16_f32 v64, v55, s0
	ds_write_b16 v210, v64 offset:1680
	v_cvt_pk_bf16_f32 v64, v40, s0
	ds_write_b16 v210, v64 offset:128
	v_cvt_pk_bf16_f32 v64, v41, s0
	ds_write_b16 v210, v64 offset:656
	v_cvt_pk_bf16_f32 v64, v42, s0
	ds_write_b16 v210, v64 offset:1184
	v_cvt_pk_bf16_f32 v64, v43, s0
	ds_write_b16 v210, v64 offset:1712
	v_cvt_pk_bf16_f32 v64, v44, s0
	ds_write_b16 v210, v64 offset:160
	v_cvt_pk_bf16_f32 v64, v45, s0
	ds_write_b16 v210, v64 offset:688
	v_cvt_pk_bf16_f32 v64, v46, s0
	s_cmp_gt_u32 s45, 3
	ds_write_b16 v210, v64 offset:1216
	v_cvt_pk_bf16_f32 v64, v47, s0
	s_cselect_b32 s30, 0x47, 3
	ds_write_b16 v210, v64 offset:1744
	v_cvt_pk_bf16_f32 v64, v36, s0
	s_add_i32 s36, s30, s42
	ds_write_b16 v210, v64 offset:192
	v_cvt_pk_bf16_f32 v64, v37, s0
	s_and_b64 s[30:31], s[22:23], exec
	ds_write_b16 v210, v64 offset:720
	v_cvt_pk_bf16_f32 v64, v38, s0
	s_cselect_b32 s30, s45, s36
	ds_write_b16 v210, v64 offset:1248
	v_cvt_pk_bf16_f32 v64, v39, s0
	s_lshl_b32 s30, s30, 6
	ds_write_b16 v210, v64 offset:1776
	v_cvt_pk_bf16_f32 v64, v0, s0
	s_ashr_i32 s31, s30, 31
	ds_write_b16 v210, v64 offset:224
	v_cvt_pk_bf16_f32 v64, v1, s0
	ds_write_b16 v210, v64 offset:752
	v_cvt_pk_bf16_f32 v64, v2, s0
	s_add_u32 s30, s44, s30
	ds_write_b16 v210, v64 offset:1280
	v_cvt_pk_bf16_f32 v64, v3, s0
	s_addc_u32 s31, s43, s31
	ds_write_b16 v210, v64 offset:1808
	s_waitcnt vmcnt(7)
	v_and_b32_e32 v231, 0xffff0000, v8
	v_lshlrev_b32_e32 v230, 16, v8
	v_and_b32_e32 v229, 0xffff0000, v4
	v_lshlrev_b32_e32 v228, 16, v4
	v_pk_mul_f32 v[232:233], v[102:103], v[230:231]
	v_and_b32_e32 v231, 0xffff0000, v5
	v_lshlrev_b32_e32 v230, 16, v5
	v_and_b32_e32 v237, 0xffff0000, v6
	v_lshlrev_b32_e32 v236, 16, v6
	v_and_b32_e32 v241, 0xffff0000, v7
	v_lshlrev_b32_e32 v240, 16, v7
	v_pk_mul_f32 v[228:229], v[100:101], v[228:229]
	v_pk_mul_f32 v[230:231], v[100:101], v[230:231]
	v_and_b32_e32 v235, 0xffff0000, v9
	v_lshlrev_b32_e32 v234, 16, v9
	v_pk_mul_f32 v[236:237], v[100:101], v[236:237]
	v_and_b32_e32 v239, 0xffff0000, v10
	v_lshlrev_b32_e32 v238, 16, v10
	v_pk_mul_f32 v[240:241], v[100:101], v[240:241]
	v_and_b32_e32 v243, 0xffff0000, v11
	v_lshlrev_b32_e32 v242, 16, v11
	v_pk_mul_f32 v[234:235], v[102:103], v[234:235]
	v_pk_mul_f32 v[238:239], v[102:103], v[238:239]
	v_pk_mul_f32 v[242:243], v[102:103], v[242:243]
	v_cvt_pk_bf16_f32 v228, v228, v229
	v_cvt_pk_bf16_f32 v229, v230, v231
	v_cvt_pk_bf16_f32 v230, v236, v237
	v_cvt_pk_bf16_f32 v231, v240, v241
	ds_write_b128 v178, v[228:231]
	v_cvt_pk_bf16_f32 v228, v232, v233
	v_cvt_pk_bf16_f32 v229, v234, v235
	v_cvt_pk_bf16_f32 v230, v238, v239
	v_cvt_pk_bf16_f32 v231, v242, v243
	ds_write_b128 v179, v[228:231]
	s_waitcnt vmcnt(5)
; #define LAS __attribute__((address_space(3)))
; __device__ __forceinline__ bf16_t f2bf(float x) { return (bf16_t)(cvt_pk_bf16(x, x) & 0xffffu); }
; __device__ __forceinline__ float bf2f(bf16_t v) { return __uint_as_float((unsigned)v << 16); }
; __device__ __forceinline__ u32x4 pack8(const float* v) { u32x4 w; w.x = cvt_pk_bf16(v[0], v[1]); w.y = cvt_pk_bf16(v[2], v[3]); w.z = cvt_pk_bf16(v[4], v[5]); w.w = cvt_pk_bf16(v[6], v[7]); return w; }
; #define GLA_BAR() do { asm volatile("s_waitcnt lgkmcnt(0)" ::: "memory"); __builtin_amdgcn_s_barrier(); asm volatile("" ::: "memory"); } while (0)
; template <int DK, int DVS, bool RET> ...
;     ...
;                 for (int j = 0; j < 4; ++j) { const int it = tid + 512 * j, p = it & 63, k0 = (it >> 6) * 8; const float bb = (float)(p + 1) * lg;
;                     const float eq = __expf(bb), ek = __expf(-bb); float a[8], c[8];
; #pragma unroll
;                     for (int e = 0; e < 8; ++e) { a[e] = bf2f((bf16_t)qv[j][e]) * eq; c[e] = bf2f((bf16_t)kv[j][e]) * ek; }
;                     *(LAS u32x4*)(QD + p * LK + k0) = pack8(a); *(LAS u32x4*)(KD + p * LK + k0) = pack8(c); }
;             } else {
;                 float c = 0.f;
; #pragma unroll
;                 for (int i = 0; i < PPT; ++i) c += lc[i];
;                 TOT[pg * 128 + kx] = c;
;                 GLA_BAR();
;                 float off = 0.f; bl = 0.f;
; #pragma unroll
;                 for (int g = 0; g < NPG; ++g) { const float t = TOT[g * 128 + kx]; if (g < pg) off += t; bl += t; }
;                 float bb = off;
; #pragma unroll
;                 for (int i = 0; i < PPT; ++i) { const int p = pg * PPT + i;
;                     const float qf = bf2f(qr[i]), kf = 1.f - __expf(lc[i]); bb += lc[i];
;                     QD[p * LK + kx] = f2bf(qf * __expf(bb)); KD[p * LK + kx] = f2bf(kf * __expf(-bb)); }
;             }
;             if (pg == 0) EL[kx] = __expf(bl);
;             { const int p = tid >> 3, vg = tid & 7; *(LAS vvec_t*)(VI + p * LV + vg * VPT) = vraw; }
;         }
;         if (step + 1 < 68) GLA_LOAD(step + 1);
	v_and_b32_e32 v231, 0xffff0000, v16
	v_lshlrev_b32_e32 v230, 16, v16
	v_and_b32_e32 v229, 0xffff0000, v12
	v_lshlrev_b32_e32 v228, 16, v12
	v_pk_mul_f32 v[232:233], v[102:103], v[230:231]
	v_and_b32_e32 v231, 0xffff0000, v13
	v_lshlrev_b32_e32 v230, 16, v13
	v_and_b32_e32 v237, 0xffff0000, v14
	v_lshlrev_b32_e32 v236, 16, v14
	v_and_b32_e32 v241, 0xffff0000, v15
	v_lshlrev_b32_e32 v240, 16, v15
	v_pk_mul_f32 v[228:229], v[100:101], v[228:229]
	v_pk_mul_f32 v[230:231], v[100:101], v[230:231]
	v_and_b32_e32 v235, 0xffff0000, v17
	v_lshlrev_b32_e32 v234, 16, v17
	v_pk_mul_f32 v[236:237], v[100:101], v[236:237]
	v_and_b32_e32 v239, 0xffff0000, v18
	v_lshlrev_b32_e32 v238, 16, v18
	v_pk_mul_f32 v[240:241], v[100:101], v[240:241]
	v_and_b32_e32 v243, 0xffff0000, v19
	v_lshlrev_b32_e32 v242, 16, v19
	v_pk_mul_f32 v[234:235], v[102:103], v[234:235]
	v_pk_mul_f32 v[238:239], v[102:103], v[238:239]
	v_pk_mul_f32 v[242:243], v[102:103], v[242:243]
	v_cvt_pk_bf16_f32 v228, v228, v229
	v_cvt_pk_bf16_f32 v229, v230, v231
	v_cvt_pk_bf16_f32 v230, v236, v237
	v_cvt_pk_bf16_f32 v231, v240, v241
	ds_write_b128 v180, v[228:231]
	v_cvt_pk_bf16_f32 v228, v232, v233
	v_cvt_pk_bf16_f32 v229, v234, v235
	v_cvt_pk_bf16_f32 v230, v238, v239
	v_cvt_pk_bf16_f32 v231, v242, v243
	ds_write_b128 v181, v[228:231]
	s_waitcnt vmcnt(3)
	v_and_b32_e32 v231, 0xffff0000, v24
	v_lshlrev_b32_e32 v230, 16, v24
	v_and_b32_e32 v229, 0xffff0000, v20
	v_lshlrev_b32_e32 v228, 16, v20
	v_pk_mul_f32 v[232:233], v[102:103], v[230:231]
	v_and_b32_e32 v231, 0xffff0000, v21
	v_lshlrev_b32_e32 v230, 16, v21
	v_and_b32_e32 v237, 0xffff0000, v22
	v_lshlrev_b32_e32 v236, 16, v22
	v_and_b32_e32 v241, 0xffff0000, v23
	v_lshlrev_b32_e32 v240, 16, v23
	v_pk_mul_f32 v[228:229], v[100:101], v[228:229]
	v_pk_mul_f32 v[230:231], v[100:101], v[230:231]
	v_and_b32_e32 v235, 0xffff0000, v25
	v_lshlrev_b32_e32 v234, 16, v25
	v_pk_mul_f32 v[236:237], v[100:101], v[236:237]
	v_and_b32_e32 v239, 0xffff0000, v26
	v_lshlrev_b32_e32 v238, 16, v26
	v_pk_mul_f32 v[240:241], v[100:101], v[240:241]
	v_and_b32_e32 v243, 0xffff0000, v27
	v_lshlrev_b32_e32 v242, 16, v27
	v_pk_mul_f32 v[234:235], v[102:103], v[234:235]
	v_pk_mul_f32 v[238:239], v[102:103], v[238:239]
	v_pk_mul_f32 v[242:243], v[102:103], v[242:243]
	v_cvt_pk_bf16_f32 v228, v228, v229
	v_cvt_pk_bf16_f32 v229, v230, v231
	v_cvt_pk_bf16_f32 v230, v236, v237
	v_cvt_pk_bf16_f32 v231, v240, v241
	ds_write_b128 v182, v[228:231]
	v_cvt_pk_bf16_f32 v228, v232, v233
	v_cvt_pk_bf16_f32 v229, v234, v235
	v_cvt_pk_bf16_f32 v230, v238, v239
	v_cvt_pk_bf16_f32 v231, v242, v243
	ds_write_b128 v183, v[228:231]
	s_waitcnt vmcnt(1)
	v_and_b32_e32 v231, 0xffff0000, v32
	v_lshlrev_b32_e32 v230, 16, v32
	v_and_b32_e32 v229, 0xffff0000, v28
	v_lshlrev_b32_e32 v228, 16, v28
	v_pk_mul_f32 v[232:233], v[102:103], v[230:231]
	v_and_b32_e32 v231, 0xffff0000, v29
	v_lshlrev_b32_e32 v230, 16, v29
	v_and_b32_e32 v237, 0xffff0000, v30
	v_lshlrev_b32_e32 v236, 16, v30
	v_and_b32_e32 v241, 0xffff0000, v31
	v_lshlrev_b32_e32 v240, 16, v31
	v_pk_mul_f32 v[228:229], v[100:101], v[228:229]
	v_pk_mul_f32 v[230:231], v[100:101], v[230:231]
	v_and_b32_e32 v235, 0xffff0000, v33
	v_lshlrev_b32_e32 v234, 16, v33
	v_pk_mul_f32 v[236:237], v[100:101], v[236:237]
	v_and_b32_e32 v239, 0xffff0000, v34
	v_lshlrev_b32_e32 v238, 16, v34
	v_pk_mul_f32 v[240:241], v[100:101], v[240:241]
	v_and_b32_e32 v243, 0xffff0000, v35
	v_lshlrev_b32_e32 v242, 16, v35
	v_pk_mul_f32 v[234:235], v[102:103], v[234:235]
	v_pk_mul_f32 v[238:239], v[102:103], v[238:239]
	v_pk_mul_f32 v[242:243], v[102:103], v[242:243]
	v_cvt_pk_bf16_f32 v228, v228, v229
	v_cvt_pk_bf16_f32 v229, v230, v231
	v_cvt_pk_bf16_f32 v230, v236, v237
	v_cvt_pk_bf16_f32 v231, v240, v241
	ds_write_b128 v184, v[228:231]
	v_cvt_pk_bf16_f32 v228, v232, v233
	v_cvt_pk_bf16_f32 v229, v234, v235
	v_cvt_pk_bf16_f32 v230, v238, v239
	v_cvt_pk_bf16_f32 v231, v242, v243
	ds_write_b128 v185, v[228:231]
	s_and_saveexec_b64 s[40:41], vcc
	ds_write_b32 v171, v173
	s_or_b64 exec, exec, s[40:41]
	s_add_i32 s36, s45, 1
	s_cmpk_eq_i32 s42, 0xffbd
	s_waitcnt vmcnt(0)
	ds_write_b128 v172, v[212:215]
	s_cbranch_scc1 .LBB0_70
	s_cmp_gt_u32 s45, 2
	s_cselect_b32 s40, 0x46, 2
	s_add_i32 s45, s40, s42
	s_and_b64 s[40:41], s[22:23], exec
	s_cselect_b32 s40, s36, s45
	s_lshl_b32 s40, s40, 6
	s_ashr_i32 s41, s40, 31
	v_lshl_add_u64 v[4:5], v[94:95], 0, s[40:41]
	v_lshlrev_b64 v[4:5], 11, v[4:5]
	v_lshl_add_u64 v[28:29], s[28:29], 0, v[4:5]
	v_lshl_add_u64 v[30:31], s[24:25], 0, v[4:5]
	v_lshl_add_u64 v[4:5], v[28:29], 0, v[86:87]
	v_lshl_add_u64 v[8:9], v[30:31], 0, v[86:87]
	v_lshl_add_u64 v[12:13], v[28:29], 0, v[88:89]
	v_lshl_add_u64 v[16:17], v[30:31], 0, v[88:89]
	v_lshl_add_u64 v[20:21], v[28:29], 0, v[90:91]
	v_lshl_add_u64 v[24:25], v[30:31], 0, v[90:91]
	v_lshl_add_u64 v[28:29], v[28:29], 0, v[92:93]
	v_lshl_add_u64 v[32:33], v[30:31], 0, v[92:93]
	global_load_dwordx4 v[4:7], v[4:5], off
	s_nop 0
	global_load_dwordx4 v[8:11], v[8:9], off
	s_nop 0
	global_load_dwordx4 v[12:15], v[12:13], off
	s_nop 0
	global_load_dwordx4 v[16:19], v[16:17], off
	s_nop 0
	global_load_dwordx4 v[20:23], v[20:21], off
	s_nop 0
	global_load_dwordx4 v[24:27], v[24:25], off
	s_nop 0
	global_load_dwordx4 v[28:31], v[28:29], off
	s_nop 0
	global_load_dwordx4 v[32:35], v[32:33], off
	s_branch .LBB0_70

; __device__ __forceinline__ int v_rd_base(int lane) { return ((lane & 3) << 3) | (((lane >> 2) & 3) << 6) | (((lane >> 4) & 1) << 5) | (((lane >> 5) & 1) << 8); }
; #define ABAR() do { asm volatile("s_waitcnt lgkmcnt(0)" ::: "memory"); __builtin_amdgcn_s_barrier(); asm volatile("" ::: "memory"); } while (0)
; template <int QH> __device__ __forceinline__ void attn_dense_body(const bf16_t* __restrict__ Qb, const bf16_t* __restrict__ Kh, const bf16_t* __restrict__ Vh,
;                                                 bf16_t* __restrict__ Ob, int seq, float scale, char* lds, const int tid) {
;     ...
;   const bf16_t* Qw = Qb + (long)(wid * QBLK + r32) * LDQ + hi * 8;
; #pragma unroll
;   for (int d0 = 0; d0 < 8; ++d0) qr[d0] = *reinterpret_cast<const bf16x8*>(Qw + d0 * 16);
;   unsigned ko[2], vo[2];
; #pragma unroll
;   for (int n = 0; n < 2; ++n) { const int d = (n * 8 + wid) * 1024 + lane * 16;
;     { const int r = d >> 8, pos = (d & 255) >> 4, c = pos ^ (r & 7); ko[n] = (unsigned)(r * LDK + c * 8) * 2u; }
;     { const int sb = d >> 9, e = d & 511, kk = (sb >> 2) * 8 + (e >> 6), k = (kk & ~0xC) | ((kk & 4) << 1) | ((kk & 8) >> 1), c = (sb & 3) * 32 + ((e & 63) >> 1); vo[n] = (unsigned)(k * LDK + c) * 2u; } }
;   const int vrb = (int)(uintptr_t)lds + 16384 + v_rd_base(lane);
;     ...
;   f32x16 pA0, pA1, pB0, pB1; float mnA, mnB, alA, alB; bf16x8 pa0, pa1, pa2, pa3; const int NT = seq / KVBLK;
;   ADMA(0); ADMA(1);
;   asm volatile("s_waitcnt vmcnt(4)" ::: "memory"); ABAR();
;   if (2 < NT) ADMA(2);
;   qkt<QH>(pA0, pA1, KSLOT(0), qr, r32, hi); partialSM(pA0, pA1, m_reg, mnA, alA, C, thr);
.LBB0_96:
	s_mul_i32 s8, s10, 0x1100
	s_lshl_b32 s12, s12, 8
	s_mul_hi_i32 s9, s10, 0x1100
	s_add_u32 s8, s8, s12
	s_addc_u32 s9, s9, 0
	s_lshl_b64 s[12:13], s[8:9], 11
	s_lshl_b32 s66, s11, 7
	s_or_b32 s16, s12, s66
	s_mul_i32 s9, s10, 0x440000
	s_lshl_b32 s15, s14, 7
	s_mul_hi_i32 s8, s10, 0x440000
	s_add_u32 s18, s9, s15
	s_mov_b32 s17, s13
	s_addc_u32 s19, s8, 0
	s_mov_b64 s[8:9], -1
	s_andn2_b64 vcc, exec, s[54:55]
	v_lshlrev_b32_e32 v144, 1, v130
	s_mul_hi_i32 s71, s10, 0x880000
	s_mul_i32 s72, s10, 0x880000
	s_cbranch_vccnz .LBB0_127
	s_lshl_b64 s[8:9], s[16:17], 1
	s_add_u32 s22, s28, s8
	s_addc_u32 s23, s29, s9
	s_lshl_b64 s[8:9], s[18:19], 1
	s_add_u32 s20, s30, s8
	s_addc_u32 s21, s31, s9
	s_add_u32 s8, s56, s8
	v_readfirstlane_b32 s10, v146
	s_addc_u32 s9, s57, s9
	s_ashr_i32 s15, s10, 6
	s_and_b32 s10, s10, 0x3fffffc0
	s_lshl_b32 s10, s10, 2
	s_add_i32 s10, s10, 0
	s_add_i32 s67, s10, 0x20000
	s_lshl_b32 s10, s15, 5
	v_or_b32_e32 v0, s10, v128
	v_ashrrev_i32_e32 v1, 31, v0
	v_lshlrev_b64 v[0:1], 12, v[0:1]
	v_lshl_add_u64 v[0:1], s[22:23], 0, v[0:1]
	v_lshl_add_u64 v[0:1], v[0:1], 0, v[144:145]
	flat_load_dwordx4 v[124:127], v[0:1] nt
	flat_load_dwordx4 v[120:123], v[0:1] offset:32 nt
	flat_load_dwordx4 v[116:119], v[0:1] offset:64 nt
	flat_load_dwordx4 v[112:115], v[0:1] offset:96 nt
	flat_load_dwordx4 v[108:111], v[0:1] offset:128 nt
	flat_load_dwordx4 v[104:107], v[0:1] offset:160 nt
	flat_load_dwordx4 v[100:103], v[0:1] offset:192 nt
	flat_load_dwordx4 v[96:99], v[0:1] offset:224 nt
	s_lshl_b32 s22, s15, 10
	s_ashr_i32 s15, s22, 8
	v_or_b32_e32 v0, s22, v129
	s_and_b32 s23, s15, 0x1ffff0
	s_lshr_b32 s15, s15, 1
	v_ashrrev_i32_e32 v1, 8, v0
	s_and_b32 s15, s15, 4
	v_bitop3_b32 v2, v1, v131, 7 bitop3:0x6c
	v_lshlrev_b32_e32 v1, 11, v1
	s_or_b32 s23, s23, s15
	v_lshl_or_b32 v48, v2, 4, v1
	v_or_b32_e32 v1, s23, v147
	v_lshrrev_b32_e32 v0, 3, v0
	s_add_i32 s15, s22, 0x2000
	v_and_b32_e32 v56, 0xc0, v0
	v_lshlrev_b32_e32 v0, 11, v1
	v_or_b32_e32 v1, s15, v129
	s_ashr_i32 s15, s15, 8
	s_and_b32 s24, s15, 0x1ffff0
	s_lshr_b32 s15, s15, 1
	s_and_b32 s15, s15, 4
	s_add_i32 s26, s22, 0
	v_ashrrev_i32_e32 v2, 8, v1
	s_or_b32 s24, s24, s15
	s_add_i32 s15, s26, 0x4000
	s_mov_b32 m0, s26
	v_or3_b32 v0, v0, v56, v172
	v_bitop3_b32 v3, v2, v131, 7 bitop3:0x6c
	v_lshlrev_b32_e32 v2, 11, v2
	global_load_lds_dwordx4 v48, s[20:21]
	s_mov_b32 m0, s15
	v_lshl_or_b32 v50, v3, 4, v2
	v_or_b32_e32 v2, s24, v147
	v_lshrrev_b32_e32 v1, 3, v1
	global_load_lds_dwordx4 v0, s[8:9]
	s_add_i32 m0, s26, 0x2000
	v_and_b32_e32 v1, 0xc0, v1
	v_lshlrev_b32_e32 v2, 11, v2
	global_load_lds_dwordx4 v50, s[20:21]
	s_add_i32 m0, s26, 0x6000
	v_or3_b32 v1, v2, v1, v172
	s_add_u32 s38, s20, 0x20000
	global_load_lds_dwordx4 v1, s[8:9]
	s_addc_u32 s39, s21, 0
	s_add_i32 m0, s26, 0x8000
	s_add_u32 s40, s8, 0x20000
	s_addc_u32 s41, s9, 0
	s_add_i32 s15, s26, 0xc000
	global_load_lds_dwordx4 v48, s[38:39]
	s_mov_b32 m0, s15
	v_add_u32_e32 v4, 0, v175
	global_load_lds_dwordx4 v0, s[40:41]
	s_add_i32 m0, s26, 0xa000
	v_add_u32_e32 v8, 0, v182
	global_load_lds_dwordx4 v50, s[38:39]
	s_add_i32 m0, s26, 0xe000
	s_add_u32 s20, s20, 0x40000
	global_load_lds_dwordx4 v1, s[40:41]
	s_addc_u32 s21, s21, 0
	s_add_i32 m0, s26, 0x10000
	s_waitcnt vmcnt(4)
	s_add_u32 s8, s8, 0x40000
	s_waitcnt lgkmcnt(0)
	s_barrier
	s_addc_u32 s9, s9, 0
	s_add_i32 s15, s26, 0x14000
	global_load_lds_dwordx4 v48, s[20:21]
	s_mov_b32 m0, s15
	s_mov_b32 s36, s37
	global_load_lds_dwordx4 v0, s[8:9]
	s_add_i32 m0, s26, 0x12000
	s_mov_b32 s38, s37
	global_load_lds_dwordx4 v50, s[20:21]
	s_add_i32 m0, s26, 0x16000
	s_mov_b32 s39, s37
	global_load_lds_dwordx4 v1, s[8:9]
	ds_read_b128 v[0:3], v4
	ds_read_b128 v[4:7], v4 offset:8192
	s_waitcnt vmcnt(0) lgkmcnt(0)
	v_mfma_f32_32x32x16_bf16 v[32:47], v[4:7], v[124:127], 0
	v_add_u32_e32 v4, 0, v176
	s_mov_b32 s40, s37
	s_mov_b32 s41, s37
	s_mov_b32 s42, s37
	s_mov_b32 s43, s37
	s_mov_b32 s44, s37
	s_mov_b32 s45, s37
	v_mfma_f32_32x32x16_bf16 v[16:31], v[0:3], v[124:127], 0
	ds_read_b128 v[0:3], v4
	ds_read_b128 v[4:7], v4 offset:8192
	s_mov_b32 s46, s37
	s_mov_b32 s47, s37
	s_mov_b32 s48, s37
	s_mov_b32 s49, s37
	s_mov_b32 s50, s37
	s_mov_b32 s51, s37
	s_waitcnt lgkmcnt(0)
	v_mfma_f32_32x32x16_bf16 v[32:47], v[4:7], v[120:123], v[32:47]
	v_add_u32_e32 v4, 0, v177
	s_mov_b32 s15, s37
	v_mov_b32_e32 v49, v145
	v_mov_b32_e32 v51, v145
	s_mov_b32 s27, 4
	s_mov_b32 s73, 0x10000
	v_lshl_add_u32 v184, v128, 2, s67
	v_mfma_f32_32x32x16_bf16 v[16:31], v[0:3], v[120:123], v[16:31]
	ds_read_b128 v[0:3], v4
	ds_read_b128 v[4:7], v4 offset:8192
	v_mov_b32_e32 v185, 0
	s_waitcnt lgkmcnt(0)
	v_mfma_f32_32x32x16_bf16 v[32:47], v[4:7], v[116:119], v[32:47]
	v_add_u32_e32 v4, 0, v178
	v_mfma_f32_32x32x16_bf16 v[16:31], v[0:3], v[116:119], v[16:31]
	ds_read_b128 v[0:3], v4
	ds_read_b128 v[4:7], v4 offset:8192
	s_waitcnt lgkmcnt(0)
	v_mfma_f32_32x32x16_bf16 v[32:47], v[4:7], v[112:115], v[32:47]
	v_add_u32_e32 v4, 0, v179
	v_mfma_f32_32x32x16_bf16 v[16:31], v[0:3], v[112:115], v[16:31]
	ds_read_b128 v[0:3], v4
	ds_read_b128 v[4:7], v4 offset:8192
	s_waitcnt lgkmcnt(0)
	v_mfma_f32_32x32x16_bf16 v[32:47], v[4:7], v[108:111], v[32:47]
	v_add_u32_e32 v4, 0, v180
	v_mfma_f32_32x32x16_bf16 v[16:31], v[0:3], v[108:111], v[16:31]
	ds_read_b128 v[0:3], v4
	ds_read_b128 v[4:7], v4 offset:8192
	ds_read_b128 v[52:55], v8 offset:8192
	s_waitcnt lgkmcnt(1)
	v_mfma_f32_32x32x16_bf16 v[32:47], v[4:7], v[104:107], v[32:47]
	v_add_u32_e32 v4, 0, v181
	v_mfma_f32_32x32x16_bf16 v[16:31], v[0:3], v[104:107], v[16:31]
	ds_read_b128 v[0:3], v4
	ds_read_b128 v[4:7], v4 offset:8192
	s_waitcnt lgkmcnt(1)
	v_mfma_f32_32x32x16_bf16 v[16:31], v[0:3], v[100:103], v[16:31]
	ds_read_b128 v[0:3], v8
	s_waitcnt vmcnt(4)
	s_waitcnt lgkmcnt(0)
	s_barrier
; __device__ __forceinline__ void partialSM(f32x16& p0, f32x16& p1, float& m_reg, float& mn, float& alpha, float C, float thr) {
;   float pmax = p0[0]; for (int r = 1; r < 16; ++r) pmax = fmaxf(pmax, p0[r]); for (int r = 0; r < 16; ++r) pmax = fmaxf(pmax, p1[r]);
;   { auto rr = __builtin_amdgcn_permlane32_swap(__float_as_uint(pmax), __float_as_uint(pmax), false, false);
;     pmax = fmaxf(__uint_as_float(rr[0]), __uint_as_float(rr[1])); }
;   if (__builtin_expect(__all(pmax - m_reg <= thr), 1)) { mn = m_reg; alpha = 1.f; }
;   else { mn = fmaxf(m_reg, pmax); alpha = __builtin_amdgcn_exp2f((m_reg - mn) * C); m_reg = mn; }
;   float mnC = -mn * C;
;   for (int r = 0; r < 16; ++r) p0[r] = fmaf(p0[r], C, mnC); for (int r = 0; r < 16; ++r) p1[r] = fmaf(p1[r], C, mnC);
;   for (int r = 0; r < 16; ++r) p0[r] = __builtin_amdgcn_exp2f(p0[r]);
; template <int QH> __device__ __forceinline__ void attn_dense_body(const bf16_t* __restrict__ Qb, const bf16_t* __restrict__ Kh, const bf16_t* __restrict__ Vh,
;                                                 bf16_t* __restrict__ Ob, int seq, float scale, char* lds, const int tid) {
;     ...
;   float m_reg = -1e30f, l_reg = 0; f32x16 o[4] = {}; bf16x8 qr[8];
	s_waitcnt lgkmcnt(1)
	v_mfma_f32_32x32x16_bf16 v[32:47], v[4:7], v[100:103], v[32:47]
	s_waitcnt lgkmcnt(0)
	v_mfma_f32_32x32x16_bf16 v[16:31], v[0:3], v[96:99], v[16:31]
	v_mov_b64_e32 v[0:1], s[36:37]
	v_mov_b64_e32 v[2:3], s[38:39]
	v_mov_b64_e32 v[4:5], s[40:41]
	v_mov_b64_e32 v[6:7], s[42:43]
	v_mov_b64_e32 v[8:9], s[44:45]
	v_mov_b64_e32 v[10:11], s[46:47]
	v_mov_b64_e32 v[12:13], s[48:49]
	v_mfma_f32_32x32x16_bf16 v[32:47], v[52:55], v[96:99], v[32:47]
	s_nop 3
	v_max_f32_e32 v52, v17, v17
	v_max_f32_e32 v53, v16, v16
	v_max_f32_e32 v52, v53, v52
	v_max3_f32 v52, v52, v18, v19
	v_max3_f32 v52, v52, v20, v21
	v_max3_f32 v52, v52, v22, v23
	v_max3_f32 v52, v52, v24, v25
	v_max3_f32 v52, v52, v26, v27
	v_max3_f32 v52, v52, v28, v29
	v_max3_f32 v52, v52, v30, v31
	v_max3_f32 v52, v52, v32, v33
	v_max3_f32 v52, v52, v34, v35
	v_max3_f32 v52, v52, v36, v37
	v_max3_f32 v52, v52, v38, v39
	v_max3_f32 v52, v52, v40, v41
	v_max3_f32 v52, v52, v42, v43
	v_max3_f32 v52, v52, v44, v45
	v_max3_f32 v52, v52, v46, v47
	v_mov_b32_e32 v53, v52
	s_nop 1
	v_permlane32_swap_b32_e32 v52, v53
	v_max_f32_e32 v53, v53, v53
	v_max_f32_e32 v52, v52, v52
	v_max_f32_e32 v52, v52, v53
	v_mov_b64_e32 v[14:15], s[50:51]
	v_add_f32_e32 v53, 0x7149f2ca, v52
	s_mov_b32 s40, 0x42b504f3
	v_cmp_ge_f32_e32 vcc, s40, v53
	s_cmp_eq_u64 vcc, exec
	v_max_f32_e32 v52, 0xf149f2ca, v52
	s_cselect_b64 vcc, -1, 0
	v_cndmask_b32_e32 v199, v52, v197, vcc
	v_sub_f32_e32 v53, 0xf149f2ca, v52
	v_mul_f32_e32 v52, 0xbe0293ee, v199
	v_fmamk_f32 v16, v16, 0x3e0293ee, v52
	v_exp_f32_e32 v209, v16
	v_fmamk_f32 v16, v17, 0x3e0293ee, v52
	v_exp_f32_e32 v210, v16
	v_fmamk_f32 v16, v18, 0x3e0293ee, v52
	v_exp_f32_e32 v211, v16
	v_fmamk_f32 v16, v19, 0x3e0293ee, v52
	v_exp_f32_e32 v213, v16
	v_fmamk_f32 v16, v20, 0x3e0293ee, v52
	v_exp_f32_e32 v215, v16
	v_fmamk_f32 v16, v21, 0x3e0293ee, v52
	v_exp_f32_e32 v216, v16
	v_fmamk_f32 v16, v22, 0x3e0293ee, v52
	v_exp_f32_e32 v212, v16
	v_fmamk_f32 v16, v23, 0x3e0293ee, v52
	v_exp_f32_e32 v214, v16
	v_fmamk_f32 v16, v24, 0x3e0293ee, v52
	v_exp_f32_e32 v201, v16
	v_fmamk_f32 v16, v25, 0x3e0293ee, v52
	v_exp_f32_e32 v203, v16
	v_fmamk_f32 v16, v26, 0x3e0293ee, v52
	v_exp_f32_e32 v205, v16
	v_fmamk_f32 v16, v27, 0x3e0293ee, v52
	v_exp_f32_e32 v207, v16
	v_fmamk_f32 v16, v28, 0x3e0293ee, v52
	v_mul_f32_e32 v53, 0x3e0293ee, v53
	v_exp_f32_e32 v202, v16
	v_fmamk_f32 v16, v29, 0x3e0293ee, v52
	v_add_u32_e32 v17, s22, v183
	v_exp_f32_e32 v53, v53
	v_exp_f32_e32 v204, v16
	v_fmamk_f32 v16, v30, 0x3e0293ee, v52
	s_lshl_b64 s[20:21], s[14:15], 8
	v_lshrrev_b32_e32 v17, 3, v17
	v_exp_f32_e32 v206, v16
	v_add_lshl_u32 v16, s24, v147, 11
	v_and_b32_e32 v17, 0xc0, v17
	s_add_u32 s8, s61, s72
	v_or3_b32 v16, v172, v16, v17
	v_mov_b32_e32 v17, v145
	s_addc_u32 s9, s62, s71
	v_lshl_add_u64 v[134:135], s[8:9], 0, v[16:17]
	v_add_lshl_u32 v16, s23, v147, 11
	v_pk_fma_f32 v[156:157], v[46:47], s[52:53], v[52:53] op_sel_hi:[1,0,0]
	v_pk_fma_f32 v[158:159], v[44:45], s[52:53], v[52:53] op_sel_hi:[1,0,0]
	v_pk_fma_f32 v[160:161], v[42:43], s[52:53], v[52:53] op_sel_hi:[1,0,0]
	v_pk_fma_f32 v[162:163], v[40:41], s[52:53], v[52:53] op_sel_hi:[1,0,0]
	v_pk_fma_f32 v[164:165], v[38:39], s[52:53], v[52:53] op_sel_hi:[1,0,0]
	v_pk_fma_f32 v[166:167], v[36:37], s[52:53], v[52:53] op_sel_hi:[1,0,0]
	v_pk_fma_f32 v[168:169], v[34:35], s[52:53], v[52:53] op_sel_hi:[1,0,0]
	v_pk_fma_f32 v[170:171], v[32:33], s[52:53], v[52:53] op_sel_hi:[1,0,0]
	v_fmac_f32_e32 v52, 0x3e0293ee, v31
	v_or3_b32 v16, v172, v16, v56
	v_exp_f32_e32 v208, v52
	v_lshl_add_u64 v[136:137], s[8:9], 0, v[16:17]
	s_add_u32 s8, s63, s72
	s_addc_u32 s9, s64, s71
	v_cndmask_b32_e64 v200, v53, 1.0, vcc
	v_lshl_add_u64 v[138:139], s[8:9], 0, v[50:51]
	v_lshl_add_u64 v[140:141], s[8:9], 0, v[48:49]
	v_mov_b64_e32 v[62:63], v[14:15]
	v_mov_b64_e32 v[46:47], v[14:15]
	v_mov_b64_e32 v[30:31], v[14:15]
	s_movk_i32 s44, 0x1000
	v_mov_b64_e32 v[60:61], v[12:13]
	v_mov_b64_e32 v[58:59], v[10:11]
	v_mov_b64_e32 v[56:57], v[8:9]
	v_mov_b64_e32 v[54:55], v[6:7]
	v_mov_b64_e32 v[52:53], v[4:5]
	v_mov_b64_e32 v[50:51], v[2:3]
	v_mov_b64_e32 v[48:49], v[0:1]
	v_mov_b64_e32 v[44:45], v[12:13]
	v_mov_b64_e32 v[42:43], v[10:11]
	v_mov_b64_e32 v[40:41], v[8:9]
	v_mov_b64_e32 v[38:39], v[6:7]
	v_mov_b64_e32 v[36:37], v[4:5]
	v_mov_b64_e32 v[34:35], v[2:3]
	v_mov_b64_e32 v[32:33], v[0:1]
	v_mov_b64_e32 v[28:29], v[12:13]
	v_mov_b64_e32 v[26:27], v[10:11]
	v_mov_b64_e32 v[24:25], v[8:9]
	v_mov_b64_e32 v[22:23], v[6:7]
	v_mov_b64_e32 v[20:21], v[4:5]
	v_mov_b64_e32 v[18:19], v[2:3]
	v_mov_b64_e32 v[16:17], v[0:1]
	s_mov_b64 s[42:43], 0x9dc9000
	s_mov_b64 s[46:47], 0x9de9000

; __device__ __forceinline__ int v_rd_base(int lane) { return ((lane & 3) << 3) | (((lane >> 2) & 3) << 6) | (((lane >> 4) & 1) << 5) | (((lane >> 5) & 1) << 8); }
; #define ABAR() do { asm volatile("s_waitcnt lgkmcnt(0)" ::: "memory"); __builtin_amdgcn_s_barrier(); asm volatile("" ::: "memory"); } while (0)
; template <int QH> __device__ __forceinline__ void attn_dense_body(const bf16_t* __restrict__ Qb, const bf16_t* __restrict__ Kh, const bf16_t* __restrict__ Vh,
;                                                 bf16_t* __restrict__ Ob, int seq, float scale, char* lds, const int tid) {
;     ...
;   const bf16_t* Qw = Qb + (long)(wid * QBLK + r32) * LDQ + hi * 8;
; #pragma unroll
;   for (int d0 = 0; d0 < 8; ++d0) qr[d0] = *reinterpret_cast<const bf16x8*>(Qw + d0 * 16);
;   unsigned ko[2], vo[2];
; #pragma unroll
;   for (int n = 0; n < 2; ++n) { const int d = (n * 8 + wid) * 1024 + lane * 16;
;     { const int r = d >> 8, pos = (d & 255) >> 4, c = pos ^ (r & 7); ko[n] = (unsigned)(r * LDK + c * 8) * 2u; }
;     { const int sb = d >> 9, e = d & 511, kk = (sb >> 2) * 8 + (e >> 6), k = (kk & ~0xC) | ((kk & 4) << 1) | ((kk & 8) >> 1), c = (sb & 3) * 32 + ((e & 63) >> 1); vo[n] = (unsigned)(k * LDK + c) * 2u; } }
;   const int vrb = (int)(uintptr_t)lds + 16384 + v_rd_base(lane);
;     ...
;   f32x16 pA0, pA1, pB0, pB1; float mnA, mnB, alA, alB; bf16x8 pa0, pa1, pa2, pa3; const int NT = seq / KVBLK;
;   ADMA(0); ADMA(1);
;   asm volatile("s_waitcnt vmcnt(4)" ::: "memory"); ABAR();
;   if (2 < NT) ADMA(2);
;   qkt<QH>(pA0, pA1, KSLOT(0), qr, r32, hi); partialSM(pA0, pA1, m_reg, mnA, alA, C, thr);
.LBB0_127:
	s_and_b64 vcc, exec, s[8:9]
	s_cbranch_vccz .LBB0_86
	s_and_b32 s10, s11, 1
	s_lshl_b64 s[8:9], s[16:17], 1
	s_add_u32 s20, s28, s8
	s_addc_u32 s21, s29, s9
	s_lshl_b64 s[8:9], s[18:19], 1
	s_add_u32 s18, s30, s8
	s_addc_u32 s19, s31, s9
	s_add_u32 s16, s56, s8
	s_addc_u32 s17, s57, s9
	s_cmp_eq_u32 s10, 0
	s_mov_b64 s[8:9], -1
	s_cbranch_scc1 .LBB0_159
	v_readfirstlane_b32 s8, v146
	s_ashr_i32 s9, s8, 6
	s_lshl_b32 s10, s9, 5
	v_or_b32_e32 v0, s10, v128
	v_ashrrev_i32_e32 v1, 31, v0
	v_lshlrev_b64 v[0:1], 12, v[0:1]
	v_lshl_add_u64 v[0:1], s[20:21], 0, v[0:1]
	v_lshl_add_u64 v[0:1], v[0:1], 0, v[144:145]
	flat_load_dwordx4 v[108:111], v[0:1] offset:128 nt
	flat_load_dwordx4 v[104:107], v[0:1] offset:160 nt
	flat_load_dwordx4 v[100:103], v[0:1] offset:192 nt
	flat_load_dwordx4 v[96:99], v[0:1] offset:224 nt
	s_and_b32 s8, s8, 0x3fffffc0
	s_lshl_b32 s8, s8, 2
	s_add_i32 s8, s8, 0
	s_add_i32 s67, s8, 0x20000
	s_lshl_b32 s8, s9, 10
	s_ashr_i32 s9, s8, 8
	v_or_b32_e32 v0, s8, v129
	s_and_b32 s15, s9, 0x1ffff0
	s_lshr_b32 s9, s9, 1
	v_ashrrev_i32_e32 v1, 8, v0
	s_and_b32 s9, s9, 4
	v_bitop3_b32 v2, v1, v131, 7 bitop3:0x6c
	v_lshlrev_b32_e32 v1, 11, v1
	s_or_b32 s9, s15, s9
	v_lshl_or_b32 v48, v2, 4, v1
	v_or_b32_e32 v1, s9, v147
	v_lshrrev_b32_e32 v0, 3, v0
	s_add_i32 s15, s8, 0x2000
	v_and_b32_e32 v56, 0xc0, v0
	v_lshlrev_b32_e32 v0, 11, v1
	v_or_b32_e32 v1, s15, v129
	s_ashr_i32 s15, s15, 8
	s_and_b32 s22, s15, 0x1ffff0
	s_lshr_b32 s15, s15, 1
	s_and_b32 s15, s15, 4
	s_add_i32 s73, s8, 0
	v_ashrrev_i32_e32 v2, 8, v1
	s_or_b32 s24, s22, s15
	s_add_i32 s15, s73, 0x4000
	s_mov_b32 m0, s73
	v_or3_b32 v0, v0, v56, v172
	v_bitop3_b32 v3, v2, v131, 7 bitop3:0x6c
	v_lshlrev_b32_e32 v2, 11, v2
	global_load_lds_dwordx4 v48, s[18:19]
	s_mov_b32 m0, s15
	v_lshl_or_b32 v50, v3, 4, v2
	v_or_b32_e32 v2, s24, v147
	v_lshrrev_b32_e32 v1, 3, v1
	global_load_lds_dwordx4 v0, s[16:17]
	s_add_i32 m0, s73, 0x2000
	v_and_b32_e32 v1, 0xc0, v1
	v_lshlrev_b32_e32 v2, 11, v2
	global_load_lds_dwordx4 v50, s[18:19]
	s_add_i32 m0, s73, 0x6000
	v_or3_b32 v1, v2, v1, v172
	s_add_u32 s22, s18, 0x20000
	global_load_lds_dwordx4 v1, s[16:17]
	s_addc_u32 s23, s19, 0
	s_add_i32 m0, s73, 0x8000
	s_add_u32 s26, s16, 0x20000
	s_addc_u32 s27, s17, 0
	s_add_i32 s15, s73, 0xc000
	global_load_lds_dwordx4 v48, s[22:23]
	s_mov_b32 m0, s15
	v_add_u32_e32 v4, 0, v179
	global_load_lds_dwordx4 v0, s[26:27]
	s_add_i32 m0, s73, 0xa000
	v_add_u32_e32 v8, 0, v182
	global_load_lds_dwordx4 v50, s[22:23]
	s_add_i32 m0, s73, 0xe000
	s_add_u32 s22, s18, 0x40000
	global_load_lds_dwordx4 v1, s[26:27]
	s_addc_u32 s23, s19, 0
	s_add_i32 m0, s73, 0x10000
	s_waitcnt vmcnt(4)
	s_add_u32 s26, s16, 0x40000
	s_waitcnt lgkmcnt(0)
	s_barrier
	s_addc_u32 s27, s17, 0
	s_add_i32 s15, s73, 0x14000
	global_load_lds_dwordx4 v48, s[22:23]
	s_mov_b32 m0, s15
	s_mov_b32 s36, s37
	global_load_lds_dwordx4 v0, s[26:27]
	s_add_i32 m0, s73, 0x12000
	s_mov_b32 s38, s37
	global_load_lds_dwordx4 v50, s[22:23]
	s_add_i32 m0, s73, 0x16000
	s_mov_b32 s39, s37
	global_load_lds_dwordx4 v1, s[26:27]
	ds_read_b128 v[0:3], v4
	ds_read_b128 v[4:7], v4 offset:8192
	s_waitcnt vmcnt(0) lgkmcnt(0)
	v_mfma_f32_32x32x16_bf16 v[32:47], v[4:7], v[108:111], 0
	v_add_u32_e32 v4, 0, v180
	s_mov_b32 s40, s37
	s_mov_b32 s41, s37
	s_mov_b32 s42, s37
	s_mov_b32 s43, s37
	s_mov_b32 s44, s37
	s_mov_b32 s45, s37
	v_mfma_f32_32x32x16_bf16 v[16:31], v[0:3], v[108:111], 0
	ds_read_b128 v[0:3], v4
	ds_read_b128 v[4:7], v4 offset:8192
	ds_read_b128 v[52:55], v8 offset:8192
	s_mov_b32 s46, s37
	s_mov_b32 s47, s37
	s_mov_b32 s48, s37
	s_mov_b32 s49, s37
	s_mov_b32 s50, s37
	s_waitcnt lgkmcnt(1)
	v_mfma_f32_32x32x16_bf16 v[32:47], v[4:7], v[104:107], v[32:47]
	v_add_u32_e32 v4, 0, v181
	s_mov_b32 s51, s37
	s_mov_b32 s15, s37
	v_mov_b32_e32 v49, v145
	v_mov_b32_e32 v51, v145
	s_mov_b32 s82, 4
	s_mov_b32 s83, 0x10000
	v_mfma_f32_32x32x16_bf16 v[16:31], v[0:3], v[104:107], v[16:31]
	ds_read_b128 v[0:3], v4
	ds_read_b128 v[4:7], v4 offset:8192
	v_lshl_add_u32 v156, v128, 2, s67
	v_mov_b32_e32 v157, 0
	s_waitcnt lgkmcnt(1)
	v_mfma_f32_32x32x16_bf16 v[16:31], v[0:3], v[100:103], v[16:31]
	ds_read_b128 v[0:3], v8
	s_waitcnt vmcnt(4)
	s_waitcnt lgkmcnt(0)
	s_barrier
; __device__ __forceinline__ void partialSM(f32x16& p0, f32x16& p1, float& m_reg, float& mn, float& alpha, float C, float thr) {
;   float pmax = p0[0]; for (int r = 1; r < 16; ++r) pmax = fmaxf(pmax, p0[r]); for (int r = 0; r < 16; ++r) pmax = fmaxf(pmax, p1[r]);
;   { auto rr = __builtin_amdgcn_permlane32_swap(__float_as_uint(pmax), __float_as_uint(pmax), false, false);
;     pmax = fmaxf(__uint_as_float(rr[0]), __uint_as_float(rr[1])); }
;   if (__builtin_expect(__all(pmax - m_reg <= thr), 1)) { mn = m_reg; alpha = 1.f; }
;   else { mn = fmaxf(m_reg, pmax); alpha = __builtin_amdgcn_exp2f((m_reg - mn) * C); m_reg = mn; }
;   float mnC = -mn * C;
;   for (int r = 0; r < 16; ++r) p0[r] = fmaf(p0[r], C, mnC); for (int r = 0; r < 16; ++r) p1[r] = fmaf(p1[r], C, mnC);
;   for (int r = 0; r < 16; ++r) p0[r] = __builtin_amdgcn_exp2f(p0[r]);
	s_waitcnt lgkmcnt(1)
	v_mfma_f32_32x32x16_bf16 v[32:47], v[4:7], v[100:103], v[32:47]
	s_waitcnt lgkmcnt(0)
	v_mfma_f32_32x32x16_bf16 v[16:31], v[0:3], v[96:99], v[16:31]
	v_mov_b64_e32 v[0:1], s[36:37]
	v_mov_b64_e32 v[2:3], s[38:39]
	v_mov_b64_e32 v[4:5], s[40:41]
	v_mov_b64_e32 v[6:7], s[42:43]
	v_mov_b64_e32 v[8:9], s[44:45]
	v_mov_b64_e32 v[10:11], s[46:47]
	v_mov_b64_e32 v[12:13], s[48:49]
	v_mfma_f32_32x32x16_bf16 v[32:47], v[52:55], v[96:99], v[32:47]
	s_nop 3
	v_max_f32_e32 v52, v17, v17
	v_max_f32_e32 v53, v16, v16
	v_max_f32_e32 v52, v53, v52
	v_max3_f32 v52, v52, v18, v19
	v_max3_f32 v52, v52, v20, v21
	v_max3_f32 v52, v52, v22, v23
	v_max3_f32 v52, v52, v24, v25
	v_max3_f32 v52, v52, v26, v27
	v_max3_f32 v52, v52, v28, v29
	v_max3_f32 v52, v52, v30, v31
	v_max3_f32 v52, v52, v32, v33
	v_max3_f32 v52, v52, v34, v35
	v_max3_f32 v52, v52, v36, v37
	v_max3_f32 v52, v52, v38, v39
	v_max3_f32 v52, v52, v40, v41
	v_max3_f32 v52, v52, v42, v43
	v_max3_f32 v52, v52, v44, v45
	v_max3_f32 v52, v52, v46, v47
	v_mov_b32_e32 v53, v52
	s_nop 1
	v_permlane32_swap_b32_e32 v52, v53
	v_max_f32_e32 v53, v53, v53
	v_max_f32_e32 v52, v52, v52
	v_max_f32_e32 v52, v52, v53
	v_mov_b64_e32 v[14:15], s[50:51]
	v_add_f32_e32 v53, 0x7149f2ca, v52
	s_mov_b32 s40, 0x41000000
	v_cmp_ge_f32_e32 vcc, s40, v53
	s_cmp_eq_u64 vcc, exec
	v_max_f32_e32 v52, 0xf149f2ca, v52
	s_cselect_b64 vcc, -1, 0
	v_cndmask_b32_e32 v158, v52, v197, vcc
	v_sub_f32_e32 v53, 0xf149f2ca, v52
	v_mul_f32_e32 v52, 0xbfb8aa3b, v158
	v_fmamk_f32 v16, v16, 0x3fb8aa3b, v52
	v_exp_f32_e32 v162, v16
	v_fmamk_f32 v16, v17, 0x3fb8aa3b, v52
	v_exp_f32_e32 v164, v16
	v_fmamk_f32 v16, v18, 0x3fb8aa3b, v52
	v_exp_f32_e32 v166, v16
	v_fmamk_f32 v16, v19, 0x3fb8aa3b, v52
	v_exp_f32_e32 v168, v16
	v_fmamk_f32 v16, v20, 0x3fb8aa3b, v52
	v_exp_f32_e32 v170, v16
	v_fmamk_f32 v16, v21, 0x3fb8aa3b, v52
	v_exp_f32_e32 v184, v16
	v_fmamk_f32 v16, v22, 0x3fb8aa3b, v52
	v_exp_f32_e32 v185, v16
	v_fmamk_f32 v16, v23, 0x3fb8aa3b, v52
	v_exp_f32_e32 v200, v16
	v_fmamk_f32 v16, v24, 0x3fb8aa3b, v52
	v_exp_f32_e32 v160, v16
	v_fmamk_f32 v16, v25, 0x3fb8aa3b, v52
	v_exp_f32_e32 v161, v16
	v_fmamk_f32 v16, v26, 0x3fb8aa3b, v52
	v_mul_f32_e32 v53, 0x3fb8aa3b, v53
	v_exp_f32_e32 v163, v16
	v_fmamk_f32 v16, v27, 0x3fb8aa3b, v52
	v_exp_f32_e32 v53, v53
	v_exp_f32_e32 v165, v16
	v_fmamk_f32 v16, v28, 0x3fb8aa3b, v52
	v_exp_f32_e32 v167, v16
	v_fmamk_f32 v16, v29, 0x3fb8aa3b, v52
	v_add_u32_e32 v17, s8, v183
	v_exp_f32_e32 v169, v16
	v_fmamk_f32 v16, v30, 0x3fb8aa3b, v52
	s_lshl_b64 s[22:23], s[14:15], 8
	v_lshrrev_b32_e32 v17, 3, v17
	v_exp_f32_e32 v171, v16
	v_add_lshl_u32 v16, s24, v147, 11
	v_and_b32_e32 v17, 0xc0, v17
	s_add_u32 s24, s61, s72
	v_pk_fma_f32 v[134:135], v[46:47], s[4:5], v[52:53] op_sel_hi:[1,0,0]
	v_pk_fma_f32 v[136:137], v[44:45], s[4:5], v[52:53] op_sel_hi:[1,0,0]
	v_pk_fma_f32 v[138:139], v[42:43], s[4:5], v[52:53] op_sel_hi:[1,0,0]
	v_pk_fma_f32 v[140:141], v[40:41], s[4:5], v[52:53] op_sel_hi:[1,0,0]
	v_pk_fma_f32 v[142:143], v[38:39], s[4:5], v[52:53] op_sel_hi:[1,0,0]
	v_pk_fma_f32 v[150:151], v[36:37], s[4:5], v[52:53] op_sel_hi:[1,0,0]
	v_pk_fma_f32 v[152:153], v[34:35], s[4:5], v[52:53] op_sel_hi:[1,0,0]
	v_pk_fma_f32 v[154:155], v[32:33], s[4:5], v[52:53] op_sel_hi:[1,0,0]
	v_fmac_f32_e32 v52, 0x3fb8aa3b, v31
	v_or3_b32 v16, v172, v16, v17
	v_mov_b32_e32 v17, v145
	s_addc_u32 s25, s62, s71
	v_exp_f32_e32 v199, v52
	v_lshl_add_u64 v[112:113], s[24:25], 0, v[16:17]
	v_add_lshl_u32 v16, s9, v147, 11
	s_add_u32 s8, s63, s72
	v_or3_b32 v16, v172, v16, v56
	s_addc_u32 s9, s64, s71
	v_cndmask_b32_e64 v159, v53, 1.0, vcc
	v_lshl_add_u64 v[114:115], s[24:25], 0, v[16:17]
	v_lshl_add_u64 v[116:117], s[8:9], 0, v[50:51]
	v_lshl_add_u64 v[118:119], s[8:9], 0, v[48:49]
	v_mov_b64_e32 v[62:63], v[14:15]
	v_mov_b64_e32 v[46:47], v[14:15]
	v_mov_b64_e32 v[30:31], v[14:15]
	s_movk_i32 s44, 0x1000
	v_mov_b64_e32 v[60:61], v[12:13]
	v_mov_b64_e32 v[58:59], v[10:11]
	v_mov_b64_e32 v[56:57], v[8:9]
	v_mov_b64_e32 v[54:55], v[6:7]
	v_mov_b64_e32 v[52:53], v[4:5]
	v_mov_b64_e32 v[50:51], v[2:3]
	v_mov_b64_e32 v[48:49], v[0:1]
	v_mov_b64_e32 v[44:45], v[12:13]
	v_mov_b64_e32 v[42:43], v[10:11]
	v_mov_b64_e32 v[40:41], v[8:9]
	v_mov_b64_e32 v[38:39], v[6:7]
	v_mov_b64_e32 v[36:37], v[4:5]
	v_mov_b64_e32 v[34:35], v[2:3]
	v_mov_b64_e32 v[32:33], v[0:1]
	v_mov_b64_e32 v[28:29], v[12:13]
	v_mov_b64_e32 v[26:27], v[10:11]
	v_mov_b64_e32 v[24:25], v[8:9]
	v_mov_b64_e32 v[22:23], v[6:7]
	v_mov_b64_e32 v[20:21], v[4:5]
	v_mov_b64_e32 v[18:19], v[2:3]
	v_mov_b64_e32 v[16:17], v[0:1]
	s_mov_b64 s[42:43], 0x9dc9000
	s_mov_b64 s[46:47], 0x9de9000

; __device__ __forceinline__ int v_rd_base(int lane) { return ((lane & 3) << 3) | (((lane >> 2) & 3) << 6) | (((lane >> 4) & 1) << 5) | (((lane >> 5) & 1) << 8); }
; #define ABAR() do { asm volatile("s_waitcnt lgkmcnt(0)" ::: "memory"); __builtin_amdgcn_s_barrier(); asm volatile("" ::: "memory"); } while (0)
; template <int QH> __device__ __forceinline__ void attn_dense_body(const bf16_t* __restrict__ Qb, const bf16_t* __restrict__ Kh, const bf16_t* __restrict__ Vh,
;                                                 bf16_t* __restrict__ Ob, int seq, float scale, char* lds, const int tid) {
;     ...
;   const bf16_t* Qw = Qb + (long)(wid * QBLK + r32) * LDQ + hi * 8;
; #pragma unroll
;   for (int d0 = 0; d0 < 8; ++d0) qr[d0] = *reinterpret_cast<const bf16x8*>(Qw + d0 * 16);
;   unsigned ko[2], vo[2];
; #pragma unroll
;   for (int n = 0; n < 2; ++n) { const int d = (n * 8 + wid) * 1024 + lane * 16;
;     { const int r = d >> 8, pos = (d & 255) >> 4, c = pos ^ (r & 7); ko[n] = (unsigned)(r * LDK + c * 8) * 2u; }
;     { const int sb = d >> 9, e = d & 511, kk = (sb >> 2) * 8 + (e >> 6), k = (kk & ~0xC) | ((kk & 4) << 1) | ((kk & 8) >> 1), c = (sb & 3) * 32 + ((e & 63) >> 1); vo[n] = (unsigned)(k * LDK + c) * 2u; } }
;   const int vrb = (int)(uintptr_t)lds + 16384 + v_rd_base(lane);
;     ...
;   f32x16 pA0, pA1, pB0, pB1; float mnA, mnB, alA, alB; bf16x8 pa0, pa1, pa2, pa3; const int NT = seq / KVBLK;
;   ADMA(0); ADMA(1);
;   asm volatile("s_waitcnt vmcnt(4)" ::: "memory"); ABAR();
;   if (2 < NT) ADMA(2);
;   qkt<QH>(pA0, pA1, KSLOT(0), qr, r32, hi); partialSM(pA0, pA1, m_reg, mnA, alA, C, thr);
.LBB0_159:
	s_and_b64 vcc, exec, s[8:9]
	s_cbranch_vccz .LBB0_86
	v_readfirstlane_b32 s8, v146
	s_ashr_i32 s9, s8, 6
	s_lshl_b32 s10, s9, 5
	v_or_b32_e32 v0, s10, v128
	v_ashrrev_i32_e32 v1, 31, v0
	v_lshlrev_b64 v[0:1], 12, v[0:1]
	v_lshl_add_u64 v[0:1], s[20:21], 0, v[0:1]
	v_lshl_add_u64 v[0:1], v[0:1], 0, v[144:145]
	flat_load_dwordx4 v[108:111], v[0:1] nt
	flat_load_dwordx4 v[104:107], v[0:1] offset:32 nt
	flat_load_dwordx4 v[100:103], v[0:1] offset:64 nt
	flat_load_dwordx4 v[96:99], v[0:1] offset:96 nt
	s_and_b32 s8, s8, 0x3fffffc0
	s_lshl_b32 s8, s8, 2
	s_add_i32 s8, s8, 0
	s_add_i32 s67, s8, 0x20000
	s_lshl_b32 s8, s9, 10
	s_ashr_i32 s9, s8, 8
	v_or_b32_e32 v0, s8, v129
	s_and_b32 s15, s9, 0x1ffff0
	s_lshr_b32 s9, s9, 1
	v_ashrrev_i32_e32 v1, 8, v0
	s_and_b32 s9, s9, 4
	v_bitop3_b32 v2, v1, v131, 7 bitop3:0x6c
	v_lshlrev_b32_e32 v1, 11, v1
	s_or_b32 s9, s15, s9
	v_lshl_or_b32 v144, v2, 4, v1
	v_or_b32_e32 v1, s9, v147
	v_lshrrev_b32_e32 v0, 3, v0
	s_add_i32 s15, s8, 0x2000
	v_and_b32_e32 v54, 0xc0, v0
	v_lshlrev_b32_e32 v0, 11, v1
	v_or_b32_e32 v1, s15, v129
	s_ashr_i32 s15, s15, 8
	s_and_b32 s20, s15, 0x1ffff0
	s_lshr_b32 s15, s15, 1
	s_and_b32 s15, s15, 4
	s_or_b32 s22, s20, s15
	s_add_i32 s20, s8, 0
	v_ashrrev_i32_e32 v2, 8, v1
	s_add_i32 s15, s20, 0x4000
	s_mov_b32 m0, s20
	v_or3_b32 v0, v0, v54, v172
	v_bitop3_b32 v3, v2, v131, 7 bitop3:0x6c
	v_lshlrev_b32_e32 v2, 11, v2
	global_load_lds_dwordx4 v144, s[18:19]
	s_mov_b32 m0, s15
	v_lshl_or_b32 v48, v3, 4, v2
	v_or_b32_e32 v2, s22, v147
	v_lshrrev_b32_e32 v1, 3, v1
	global_load_lds_dwordx4 v0, s[16:17]
	s_add_i32 m0, s20, 0x2000
	v_and_b32_e32 v1, 0xc0, v1
	v_lshlrev_b32_e32 v2, 11, v2
	global_load_lds_dwordx4 v48, s[18:19]
	s_add_i32 m0, s20, 0x6000
	v_or3_b32 v1, v2, v1, v172
	s_add_u32 s24, s18, 0x20000
	global_load_lds_dwordx4 v1, s[16:17]
	s_addc_u32 s25, s19, 0
	s_add_i32 m0, s20, 0x8000
	s_add_u32 s26, s16, 0x20000
	s_addc_u32 s27, s17, 0
	s_add_i32 s15, s20, 0xc000
	global_load_lds_dwordx4 v144, s[24:25]
	s_mov_b32 m0, s15
	v_add_u32_e32 v4, 0, v175
	global_load_lds_dwordx4 v0, s[26:27]
	s_add_i32 m0, s20, 0xa000
	v_add_u32_e32 v8, 0, v178
	global_load_lds_dwordx4 v48, s[24:25]
	s_add_i32 m0, s20, 0xe000
	s_add_u32 s18, s18, 0x40000
	global_load_lds_dwordx4 v1, s[26:27]
	s_addc_u32 s19, s19, 0
	s_add_i32 m0, s20, 0x10000
	s_waitcnt vmcnt(4)
	s_add_u32 s16, s16, 0x40000
	s_waitcnt lgkmcnt(0)
	s_barrier
	s_addc_u32 s17, s17, 0
	s_add_i32 s15, s20, 0x14000
	global_load_lds_dwordx4 v144, s[18:19]
	s_mov_b32 m0, s15
	s_mov_b32 s26, 0x41000000
	global_load_lds_dwordx4 v0, s[16:17]
	s_add_i32 m0, s20, 0x12000
	s_mov_b32 s15, s37
	global_load_lds_dwordx4 v48, s[18:19]
	s_add_i32 m0, s20, 0x16000
	s_mov_b32 s36, s37
	global_load_lds_dwordx4 v1, s[16:17]
	ds_read_b128 v[0:3], v4
	ds_read_b128 v[4:7], v4 offset:8192
	s_waitcnt vmcnt(0) lgkmcnt(0)
	v_mfma_f32_32x32x16_bf16 v[32:47], v[4:7], v[108:111], 0
	v_add_u32_e32 v4, 0, v176
	s_mov_b32 s38, s37
	s_mov_b32 s39, s37
	s_mov_b32 s40, s37
	s_mov_b32 s41, s37
	s_mov_b32 s42, s37
	s_mov_b32 s43, s37
	v_mfma_f32_32x32x16_bf16 v[16:31], v[0:3], v[108:111], 0
	ds_read_b128 v[0:3], v4
	ds_read_b128 v[4:7], v4 offset:8192
	ds_read_b128 v[50:53], v8 offset:8192
	s_mov_b32 s44, s37
	s_mov_b32 s45, s37
	s_mov_b32 s46, s37
	s_mov_b32 s47, s37
	s_mov_b32 s48, s37
	s_waitcnt lgkmcnt(1)
	v_mfma_f32_32x32x16_bf16 v[32:47], v[4:7], v[104:107], v[32:47]
	v_add_u32_e32 v4, 0, v177
	s_mov_b32 s49, s37
	s_mov_b32 s50, s37
	s_mov_b32 s51, s37
	v_mov_b32_e32 v49, v145
	s_mov_b32 s21, 4
	s_mov_b32 s23, 0x10000
	v_mfma_f32_32x32x16_bf16 v[16:31], v[0:3], v[104:107], v[16:31]
	ds_read_b128 v[0:3], v4
	ds_read_b128 v[4:7], v4 offset:8192
	v_lshl_add_u32 v156, v128, 2, s67
	s_waitcnt lgkmcnt(1)
	v_mfma_f32_32x32x16_bf16 v[16:31], v[0:3], v[100:103], v[16:31]
	ds_read_b128 v[0:3], v8
	s_waitcnt vmcnt(4)
	s_waitcnt lgkmcnt(0)
	s_barrier
; __device__ __forceinline__ void partialSM(f32x16& p0, f32x16& p1, float& m_reg, float& mn, float& alpha, float C, float thr) {
;   float pmax = p0[0]; for (int r = 1; r < 16; ++r) pmax = fmaxf(pmax, p0[r]); for (int r = 0; r < 16; ++r) pmax = fmaxf(pmax, p1[r]);
;   { auto rr = __builtin_amdgcn_permlane32_swap(__float_as_uint(pmax), __float_as_uint(pmax), false, false);
;     pmax = fmaxf(__uint_as_float(rr[0]), __uint_as_float(rr[1])); }
;   if (__builtin_expect(__all(pmax - m_reg <= thr), 1)) { mn = m_reg; alpha = 1.f; }
;   else { mn = fmaxf(m_reg, pmax); alpha = __builtin_amdgcn_exp2f((m_reg - mn) * C); m_reg = mn; }
;   float mnC = -mn * C;
;   for (int r = 0; r < 16; ++r) p0[r] = fmaf(p0[r], C, mnC); for (int r = 0; r < 16; ++r) p1[r] = fmaf(p1[r], C, mnC);
;   for (int r = 0; r < 16; ++r) p0[r] = __builtin_amdgcn_exp2f(p0[r]);
; }
; template <int QH> __device__ __forceinline__ void attn_dense_body(const bf16_t* __restrict__ Qb, const bf16_t* __restrict__ Kh, const bf16_t* __restrict__ Vh,
;                                                 bf16_t* __restrict__ Ob, int seq, float scale, char* lds, const int tid) {
;     ...
;   float m_reg = -1e30f, l_reg = 0; f32x16 o[4] = {}; bf16x8 qr[8];
	s_waitcnt lgkmcnt(1)
	v_mfma_f32_32x32x16_bf16 v[32:47], v[4:7], v[100:103], v[32:47]
	s_waitcnt lgkmcnt(0)
	v_mfma_f32_32x32x16_bf16 v[16:31], v[0:3], v[96:99], v[16:31]
	v_mov_b64_e32 v[0:1], s[36:37]
	v_mov_b64_e32 v[14:15], s[50:51]
	v_mov_b64_e32 v[2:3], s[38:39]
	v_mov_b64_e32 v[4:5], s[40:41]
	v_mov_b64_e32 v[6:7], s[42:43]
	v_mov_b64_e32 v[8:9], s[44:45]
	v_mov_b64_e32 v[10:11], s[46:47]
	v_mfma_f32_32x32x16_bf16 v[32:47], v[50:53], v[96:99], v[32:47]
	s_nop 3
	v_max_f32_e32 v50, v17, v17
	v_max_f32_e32 v51, v16, v16
	v_max_f32_e32 v50, v51, v50
	v_max3_f32 v50, v50, v18, v19
	v_max3_f32 v50, v50, v20, v21
	v_max3_f32 v50, v50, v22, v23
	v_max3_f32 v50, v50, v24, v25
	v_max3_f32 v50, v50, v26, v27
	v_max3_f32 v50, v50, v28, v29
	v_max3_f32 v50, v50, v30, v31
	v_max3_f32 v50, v50, v32, v33
	v_max3_f32 v50, v50, v34, v35
	v_max3_f32 v50, v50, v36, v37
	v_max3_f32 v50, v50, v38, v39
	v_max3_f32 v50, v50, v40, v41
	v_max3_f32 v50, v50, v42, v43
	v_max3_f32 v50, v50, v44, v45
	v_max3_f32 v50, v50, v46, v47
	v_mov_b32_e32 v51, v50
	s_nop 1
	v_permlane32_swap_b32_e32 v50, v51
	v_max_f32_e32 v51, v51, v51
	v_max_f32_e32 v50, v50, v50
	v_max_f32_e32 v50, v50, v51
	v_add_f32_e32 v51, 0x7149f2ca, v50
	v_cmp_ge_f32_e32 vcc, s26, v51
	s_cmp_eq_u64 vcc, exec
	v_max_f32_e32 v50, 0xf149f2ca, v50
	s_cselect_b64 vcc, -1, 0
	v_cndmask_b32_e32 v157, v50, v197, vcc
	v_sub_f32_e32 v51, 0xf149f2ca, v50
	v_mul_f32_e32 v50, 0xbfb8aa3b, v157
	v_fmamk_f32 v16, v16, 0x3fb8aa3b, v50
	v_exp_f32_e32 v161, v16
	v_fmamk_f32 v16, v17, 0x3fb8aa3b, v50
	v_exp_f32_e32 v163, v16
	v_fmamk_f32 v16, v18, 0x3fb8aa3b, v50
	v_exp_f32_e32 v165, v16
	v_fmamk_f32 v16, v19, 0x3fb8aa3b, v50
	v_exp_f32_e32 v167, v16
	v_fmamk_f32 v16, v20, 0x3fb8aa3b, v50
	v_exp_f32_e32 v169, v16
	v_fmamk_f32 v16, v21, 0x3fb8aa3b, v50
	v_exp_f32_e32 v171, v16
	v_fmamk_f32 v16, v22, 0x3fb8aa3b, v50
	v_exp_f32_e32 v184, v16
	v_fmamk_f32 v16, v23, 0x3fb8aa3b, v50
	v_exp_f32_e32 v199, v16
	v_fmamk_f32 v16, v24, 0x3fb8aa3b, v50
	v_exp_f32_e32 v159, v16
	v_fmamk_f32 v16, v25, 0x3fb8aa3b, v50
	v_exp_f32_e32 v160, v16
	v_fmamk_f32 v16, v26, 0x3fb8aa3b, v50
	v_mul_f32_e32 v51, 0x3fb8aa3b, v51
	v_exp_f32_e32 v162, v16
	v_fmamk_f32 v16, v27, 0x3fb8aa3b, v50
	v_exp_f32_e32 v51, v51
	v_exp_f32_e32 v164, v16
	v_fmamk_f32 v16, v28, 0x3fb8aa3b, v50
	v_exp_f32_e32 v166, v16
	v_fmamk_f32 v16, v29, 0x3fb8aa3b, v50
	v_add_u32_e32 v17, s8, v183
	v_exp_f32_e32 v168, v16
	v_fmamk_f32 v16, v30, 0x3fb8aa3b, v50
	s_lshl_b64 s[14:15], s[14:15], 8
	v_lshrrev_b32_e32 v17, 3, v17
	v_exp_f32_e32 v170, v16
	v_add_lshl_u32 v16, s22, v147, 11
	v_and_b32_e32 v17, 0xc0, v17
	s_add_u32 s16, s61, s72
	v_pk_fma_f32 v[134:135], v[46:47], s[4:5], v[50:51] op_sel_hi:[1,0,0]
	v_pk_fma_f32 v[136:137], v[44:45], s[4:5], v[50:51] op_sel_hi:[1,0,0]
	v_pk_fma_f32 v[138:139], v[42:43], s[4:5], v[50:51] op_sel_hi:[1,0,0]
	v_pk_fma_f32 v[140:141], v[40:41], s[4:5], v[50:51] op_sel_hi:[1,0,0]
	v_pk_fma_f32 v[142:143], v[38:39], s[4:5], v[50:51] op_sel_hi:[1,0,0]
	v_pk_fma_f32 v[150:151], v[36:37], s[4:5], v[50:51] op_sel_hi:[1,0,0]
	v_pk_fma_f32 v[152:153], v[34:35], s[4:5], v[50:51] op_sel_hi:[1,0,0]
	v_pk_fma_f32 v[154:155], v[32:33], s[4:5], v[50:51] op_sel_hi:[1,0,0]
	v_fmac_f32_e32 v50, 0x3fb8aa3b, v31
	v_or3_b32 v16, v172, v16, v17
	v_mov_b32_e32 v17, v145
	s_addc_u32 s17, s62, s71
	v_exp_f32_e32 v185, v50
	v_lshl_add_u64 v[112:113], s[16:17], 0, v[16:17]
	v_add_lshl_u32 v16, s9, v147, 11
	s_add_u32 s8, s63, s72
	v_or3_b32 v16, v172, v16, v54
	s_addc_u32 s9, s64, s71
	v_mov_b64_e32 v[12:13], s[48:49]
	v_cndmask_b32_e64 v158, v51, 1.0, vcc
	v_lshl_add_u64 v[114:115], s[16:17], 0, v[16:17]
	v_lshl_add_u64 v[116:117], s[8:9], 0, v[48:49]
	v_mov_b64_e32 v[62:63], v[14:15]
	v_mov_b64_e32 v[46:47], v[14:15]
	v_mov_b64_e32 v[30:31], v[14:15]
	s_movk_i32 s44, 0x1000
	v_lshl_add_u64 v[118:119], s[8:9], 0, v[144:145]
	v_mov_b32_e32 v144, 0
	v_mov_b64_e32 v[60:61], v[12:13]
	v_mov_b64_e32 v[58:59], v[10:11]
	v_mov_b64_e32 v[56:57], v[8:9]
	v_mov_b64_e32 v[54:55], v[6:7]
	v_mov_b64_e32 v[52:53], v[4:5]
	v_mov_b64_e32 v[50:51], v[2:3]
	v_mov_b64_e32 v[48:49], v[0:1]
	v_mov_b64_e32 v[44:45], v[12:13]
	v_mov_b64_e32 v[42:43], v[10:11]
	v_mov_b64_e32 v[40:41], v[8:9]
	v_mov_b64_e32 v[38:39], v[6:7]
	v_mov_b64_e32 v[36:37], v[4:5]
	v_mov_b64_e32 v[34:35], v[2:3]
	v_mov_b64_e32 v[32:33], v[0:1]
	v_mov_b64_e32 v[28:29], v[12:13]
	v_mov_b64_e32 v[26:27], v[10:11]
	v_mov_b64_e32 v[24:25], v[8:9]
	v_mov_b64_e32 v[22:23], v[6:7]
	v_mov_b64_e32 v[20:21], v[4:5]
	v_mov_b64_e32 v[18:19], v[2:3]
	v_mov_b64_e32 v[16:17], v[0:1]
	s_mov_b64 s[38:39], 0x9dc9000
	s_mov_b64 s[40:41], 0x9de9000
